# stagger by XCD id (8 groups, delay = xcd*d): P7 d~2.4us, P10 d~1.6us, P9 d~0.45us
# baseline (speedup 1.0000x reference)
.LBB0_1069:
	s_add_u32 s77, s74, 0x2000
	s_waitcnt vmcnt(0)
	v_lshrrev_b32_e32 v18, 1, v10
	s_addc_u32 s78, s75, 0
	v_and_b32_e32 v18, 24, v18
	s_lshl_b32 s0, s0, 5
	v_and_b32_e32 v17, 15, v10
	v_lshlrev_b32_e32 v19, 1, v18
	v_lshlrev_b32_e32 v10, 2, v10
	s_and_b32 s6, s0, 0x60
	s_add_i32 m0, s19, 0x18000
	v_lshl_add_u64 v[8:9], v[8:9], 0, s[56:57]
	v_lshl_or_b32 v188, s1, 6, v17
	v_lshl_or_b32 v17, v17, 6, v19
	s_lshl_b32 s1, s1, 13
	v_and_b32_e32 v10, 32, v10
	s_lshl_b32 s0, s6, 7
	s_waitcnt vmcnt(4)
	s_barrier
	global_load_lds_dwordx4 v[8:9], off
	v_lshl_add_u64 v[6:7], v[6:7], 0, s[56:57]
	s_add_i32 m0, s19, 0x1a000
	s_add_i32 s79, s19, 0x8000
	s_add_i32 s80, s19, 0xa000
	v_bitop3_b32 v189, v17, s0, v10 bitop3:0xde
	global_load_lds_dwordx4 v[6:7], off
	v_lshl_add_u64 v[4:5], v[4:5], 0, s[56:57]
	s_mov_b32 m0, s79
	s_add_u32 s0, s22, 0x40080
	v_bitop3_b32 v19, v17, s1, v10 bitop3:0xde
	global_load_lds_dwordx4 v[4:5], off
	v_lshl_add_u64 v[2:3], v[2:3], 0, s[56:57]
	s_mov_b32 m0, s80
	s_addc_u32 s1, s23, 0
	global_load_lds_dwordx4 v[2:3], off
	s_add_i32 m0, s19, 0x1c000
	v_lshl_add_u64 v[2:3], s[0:1], 0, v[0:1]
	global_load_lds_dwordx4 v[2:3], off
	v_lshl_add_u64 v[2:3], s[0:1], 0, v[170:171]
	s_add_i32 m0, s19, 0x1e000
	v_or_b32_e32 v190, s6, v18
	global_load_lds_dwordx4 v[2:3], off
	v_lshlrev_b32_e32 v2, 14, v11
	v_and_b32_e32 v2, 0xffff8000, v2
	v_lshl_add_u32 v2, v12, 11, v2
	v_and_b32_e32 v3, 1, v11
	v_lshl_or_b32 v2, v3, 6, v2
	v_lshl_add_u32 v172, v13, 1, v2
	v_lshlrev_b32_e32 v2, 14, v14
	v_and_b32_e32 v2, 0xffff8000, v2
	s_waitcnt vmcnt(6)
	v_lshl_add_u32 v2, v15, 11, v2
	v_and_b32_e32 v3, 1, v14
	v_lshl_or_b32 v2, v3, 6, v2
	v_mov_b32_e32 v173, v1
	v_lshl_add_u32 v174, v16, 1, v2
	v_mov_b32_e32 v175, v1
	s_mov_b32 s81, 0
	v_add_u32_e32 v191, 0, v19
	s_barrier
	s_bitcmp1_b32 s54, 0
	s_cbranch_scc0 .Lstg_p7_0
	s_sleep 88
.Lstg_p7_0:
	s_bitcmp1_b32 s54, 1
	s_cbranch_scc0 .Lstg_p7_1
	s_sleep 88
	s_sleep 88
.Lstg_p7_1:
	s_bitcmp1_b32 s54, 2
	s_cbranch_scc0 .Lstg_p7_2
	s_sleep 88
	s_sleep 88
	s_sleep 88
	s_sleep 88

.LBB0_1201:
	v_lshrrev_b32_e32 v18, 1, v6
	v_and_b32_e32 v18, 24, v18
	v_and_b32_e32 v9, 15, v6
	v_lshlrev_b32_e32 v19, 1, v18
	v_lshlrev_b32_e32 v6, 2, v6
	v_lshl_or_b32 v142, s0, 6, v9
	v_lshl_or_b32 v9, v9, 6, v19
	s_lshl_b32 s0, s0, 13
	v_and_b32_e32 v6, 32, v6
	v_lshl_add_u64 v[10:11], s[34:35], 0, v[0:1]
	v_mov_b32_e32 v135, v1
	v_bitop3_b32 v19, v9, s0, v6 bitop3:0xde
	s_lshl_b32 s0, s1, 5
	v_lshl_add_u64 v[12:13], s[34:35], 0, v[134:135]
	v_mov_b32_e32 v131, v1
	s_and_b32 s10, s0, 0x60
	s_add_i32 m0, s19, 0x18000
	v_lshl_add_u64 v[10:11], v[10:11], 0, s[56:57]
	v_lshl_add_u64 v[14:15], s[22:23], 0, v[130:131]
	v_mov_b32_e32 v133, v1
	s_lshl_b32 s0, s10, 7
	s_waitcnt vmcnt(4)
	s_barrier
	global_load_lds_dwordx4 v[10:11], off
	v_lshl_add_u64 v[10:11], v[12:13], 0, s[56:57]
	s_add_i32 m0, s19, 0x1a000
	s_add_i32 s76, s19, 0x8000
	s_add_i32 s77, s19, 0xa000
	v_lshl_add_u64 v[16:17], s[22:23], 0, v[132:133]
	v_bitop3_b32 v143, v9, s0, v6 bitop3:0xde
	global_load_lds_dwordx4 v[10:11], off
	v_lshl_add_u64 v[10:11], v[14:15], 0, s[56:57]
	s_mov_b32 m0, s76
	s_add_u32 s0, s34, 0x40080
	global_load_lds_dwordx4 v[10:11], off
	v_lshl_add_u64 v[10:11], v[16:17], 0, s[56:57]
	s_mov_b32 m0, s77
	s_addc_u32 s1, s35, 0
	global_load_lds_dwordx4 v[10:11], off
	s_add_i32 m0, s19, 0x1c000
	v_lshl_add_u64 v[10:11], s[0:1], 0, v[0:1]
	global_load_lds_dwordx4 v[10:11], off
	v_lshl_add_u64 v[10:11], s[0:1], 0, v[134:135]
	s_add_i32 m0, s19, 0x1e000
	v_lshlrev_b32_e32 v6, 14, v2
	global_load_lds_dwordx4 v[10:11], off
	v_and_b32_e32 v6, 0xffff8000, v6
	v_lshl_add_u32 v3, v3, 11, v6
	v_and_b32_e32 v2, 1, v2
	v_lshl_or_b32 v2, v2, 6, v3
	v_lshl_add_u32 v136, v4, 1, v2
	v_lshlrev_b32_e32 v2, 14, v5
	v_and_b32_e32 v2, 0xffff8000, v2
	s_waitcnt vmcnt(6)
	v_readlane_b32 s36, v252, 0
	v_lshl_add_u32 v2, v7, 11, v2
	v_and_b32_e32 v3, 1, v5
	v_readlane_b32 s37, v252, 1
	v_lshl_or_b32 v2, v3, 6, v2
	s_mov_b32 s7, s37
	v_or_b32_e32 v144, s10, v18
	v_mov_b32_e32 v137, v1
	v_lshl_add_u32 v138, v8, 1, v2
	v_mov_b32_e32 v139, v1
	s_mov_b32 s78, 0
	v_add_u32_e32 v145, 0, v19
	s_barrier
	v_readlane_b32 s38, v252, 2
	v_readlane_b32 s39, v252, 3
	v_readlane_b32 s40, v252, 4
	v_readlane_b32 s41, v252, 5
	v_readlane_b32 s42, v252, 6
	v_readlane_b32 s43, v252, 7
	v_readlane_b32 s44, v252, 8
	v_readlane_b32 s45, v252, 9
	v_readlane_b32 s46, v252, 10
	v_readlane_b32 s47, v252, 11
	v_readlane_b32 s48, v252, 12
	v_readlane_b32 s49, v252, 13
	v_readlane_b32 s50, v252, 14
	v_readlane_b32 s51, v252, 15
	s_bitcmp1_b32 s54, 0
	s_cbranch_scc0 .Lstg_p9_0
	s_sleep 16
.Lstg_p9_0:
	s_bitcmp1_b32 s54, 1
	s_cbranch_scc0 .Lstg_p9_1
	s_sleep 32
.Lstg_p9_1:
	s_bitcmp1_b32 s54, 2
	s_cbranch_scc0 .Lstg_p9_2
	s_sleep 64

.LBB0_1268:
	s_add_u32 s35, s74, 0x5000
	v_lshrrev_b32_e32 v20, 1, v10
	s_addc_u32 s61, s75, 0
	v_and_b32_e32 v20, 24, v20
	s_lshl_b32 s0, s0, 5
	v_and_b32_e32 v19, 15, v10
	v_lshlrev_b32_e32 v21, 1, v20
	v_lshlrev_b32_e32 v10, 2, v10
	s_and_b32 s6, s0, 0x60
	s_add_i32 m0, s25, 0x18000
	v_lshl_add_u64 v[8:9], v[8:9], 0, s[56:57]
	v_lshl_or_b32 v190, s1, 6, v19
	v_lshl_or_b32 v19, v19, 6, v21
	s_lshl_b32 s1, s1, 13
	v_and_b32_e32 v10, 32, v10
	s_lshl_b32 s0, s6, 7
	s_waitcnt vmcnt(4)
	s_barrier
	global_load_lds_dwordx4 v[8:9], off
	v_lshl_add_u64 v[6:7], v[6:7], 0, s[56:57]
	s_add_i32 m0, s25, 0x1a000
	s_add_i32 s62, s25, 0x8000
	s_add_i32 s63, s25, 0xa000
	v_bitop3_b32 v191, v19, s0, v10 bitop3:0xde
	global_load_lds_dwordx4 v[6:7], off
	v_lshl_add_u64 v[4:5], v[4:5], 0, s[56:57]
	s_mov_b32 m0, s62
	s_add_u32 s0, s16, 0xb0080
	v_bitop3_b32 v21, v19, s1, v10 bitop3:0xde
	global_load_lds_dwordx4 v[4:5], off
	v_lshl_add_u64 v[2:3], v[2:3], 0, s[56:57]
	s_mov_b32 m0, s63
	s_addc_u32 s1, s17, 0
	global_load_lds_dwordx4 v[2:3], off
	s_add_i32 m0, s25, 0x1c000
	v_lshl_add_u64 v[2:3], s[0:1], 0, v[0:1]
	global_load_lds_dwordx4 v[2:3], off
	v_lshl_add_u64 v[2:3], s[0:1], 0, v[170:171]
	s_add_i32 m0, s25, 0x1e000
	v_or_b32_e32 v192, s6, v20
	global_load_lds_dwordx4 v[2:3], off
	s_movk_i32 s6, 0xb00
	v_lshrrev_b32_e32 v3, 1, v11
	v_mul_lo_u32 v2, v13, s6
	s_mov_b32 s7, 0xb000
	v_mad_u64_u32 v[2:3], s[0:1], v3, s7, v[2:3]
	v_or_b32_e32 v2, v2, v12
	v_add_lshl_u32 v2, v2, v14, 1
	v_mov_b32_e32 v3, v1
	s_mov_b64 s[8:9], 0xb0080
	v_lshl_add_u64 v[172:173], v[2:3], 0, s[8:9]
	v_lshrrev_b32_e32 v3, 1, v15
	v_mul_lo_u32 v2, v17, s6
	v_mad_u64_u32 v[2:3], s[0:1], v3, s7, v[2:3]
	s_waitcnt vmcnt(6)
	v_or_b32_e32 v2, v2, v16
	v_add_lshl_u32 v2, v2, v18, 1
	v_mov_b32_e32 v3, v1
	v_lshl_add_u64 v[174:175], v[2:3], 0, s[8:9]
	s_mov_b32 s64, 0
	v_add_u32_e32 v193, 0, v21
	s_barrier
	s_bitcmp1_b32 s54, 0
	s_cbranch_scc0 .Lstg_p10_0
	s_sleep 56
.Lstg_p10_0:
	s_bitcmp1_b32 s54, 1
	s_cbranch_scc0 .Lstg_p10_1
	s_sleep 56
	s_sleep 56
.Lstg_p10_1:
	s_bitcmp1_b32 s54, 2
	s_cbranch_scc0 .Lstg_p10_2
	s_sleep 56
	s_sleep 56
	s_sleep 56
	s_sleep 56
